# FFN-in SwiGLU epilogue stores write-through (sc1, 16-byte) so the XCD L2 holds fewer dirty lines at the following barrier's write-back
# baseline (speedup 1.0000x reference)
.LBB0_216:
	v_lshl_add_u32 v181, s1, 8, v154
	v_lshl_or_b32 v170, s0, 7, v156
	v_readlane_b32 s0, v254, 45
	v_readlane_b32 s1, v254, 46
	s_movk_i32 s3, 0x1600
	s_mov_b64 s[68:69], 0x16000
	s_mov_b64 s[70:71], 0x6e000
	s_andn2_b64 vcc, exec, s[42:43]
	s_mov_b64 s[16:17], -1
	v_ashrrev_i32_e32 v171, 31, v170
	v_mov_b64_e32 v[152:153], s[0:1]
	v_lshlrev_b64 v[170:171], 1, v[170:171]
	v_mad_i64_i32 v[182:183], s[0:1], v181, s3, v[152:153]
	s_nop 0
	v_lshl_add_u64 v[182:183], v[182:183], 0, v[170:171]
	v_exp_f32_e64 v152, -v124
	v_exp_f32_e64 v153, -v125
	v_exp_f32_e64 v178, -v126
	v_exp_f32_e64 v179, -v127
	v_exp_f32_e64 v246, -v120
	v_exp_f32_e64 v247, -v121
	v_exp_f32_e64 v248, -v122
	v_exp_f32_e64 v249, -v123
	v_mul_f32_e32 v124, v124, v116
	v_mul_f32_e32 v125, v125, v117
	v_mul_f32_e32 v126, v126, v118
	v_mul_f32_e32 v127, v127, v119
	v_mul_f32_e32 v120, v120, v112
	v_mul_f32_e32 v121, v121, v113
	v_mul_f32_e32 v122, v122, v114
	v_mul_f32_e32 v123, v123, v115
	v_add_f32_e32 v152, 1.0, v152
	v_add_f32_e32 v153, 1.0, v153
	v_add_f32_e32 v178, 1.0, v178
	v_add_f32_e32 v179, 1.0, v179
	v_add_f32_e32 v246, 1.0, v246
	v_add_f32_e32 v247, 1.0, v247
	v_add_f32_e32 v248, 1.0, v248
	v_add_f32_e32 v249, 1.0, v249
	v_rcp_f32_e32 v152, v152
	v_rcp_f32_e32 v153, v153
	v_rcp_f32_e32 v178, v178
	v_rcp_f32_e32 v179, v179
	v_rcp_f32_e32 v246, v246
	v_rcp_f32_e32 v247, v247
	v_rcp_f32_e32 v248, v248
	v_rcp_f32_e32 v249, v249
	v_mul_f32_e32 v124, v124, v152
	v_mul_f32_e32 v125, v125, v153
	v_mul_f32_e32 v126, v126, v178
	v_mul_f32_e32 v127, v127, v179
	v_mul_f32_e32 v120, v120, v246
	v_mul_f32_e32 v121, v121, v247
	v_mul_f32_e32 v122, v122, v248
	v_mul_f32_e32 v123, v123, v249
	v_cvt_pk_bf16_f32 v116, v124, v125
	v_cvt_pk_bf16_f32 v117, v126, v127
	v_cvt_pk_bf16_f32 v118, v120, v121
	v_cvt_pk_bf16_f32 v119, v122, v123
	global_store_dwordx4 v[182:183], v[116:119], off sc1
	v_exp_f32_e64 v152, -v108
	v_exp_f32_e64 v153, -v109
	v_exp_f32_e64 v178, -v110
	v_exp_f32_e64 v179, -v111
	v_exp_f32_e64 v246, -v104
	v_exp_f32_e64 v247, -v105
	v_exp_f32_e64 v248, -v106
	v_exp_f32_e64 v249, -v107
	v_mul_f32_e32 v108, v108, v100
	v_mul_f32_e32 v109, v109, v101
	v_mul_f32_e32 v110, v110, v102
	v_mul_f32_e32 v111, v111, v103
	v_mul_f32_e32 v104, v104, v96
	v_mul_f32_e32 v105, v105, v97
	v_mul_f32_e32 v106, v106, v98
	v_mul_f32_e32 v107, v107, v99
	v_add_f32_e32 v152, 1.0, v152
	v_add_f32_e32 v153, 1.0, v153
	v_add_f32_e32 v178, 1.0, v178
	v_add_f32_e32 v179, 1.0, v179
	v_add_f32_e32 v246, 1.0, v246
	v_add_f32_e32 v247, 1.0, v247
	v_add_f32_e32 v248, 1.0, v248
	v_add_f32_e32 v249, 1.0, v249
	v_rcp_f32_e32 v152, v152
	v_rcp_f32_e32 v153, v153
	v_rcp_f32_e32 v178, v178
	v_rcp_f32_e32 v179, v179
	v_rcp_f32_e32 v246, v246
	v_rcp_f32_e32 v247, v247
	v_rcp_f32_e32 v248, v248
	v_rcp_f32_e32 v249, v249
	v_mul_f32_e32 v108, v108, v152
	v_mul_f32_e32 v109, v109, v153
	v_mul_f32_e32 v110, v110, v178
	v_mul_f32_e32 v111, v111, v179
	v_mul_f32_e32 v104, v104, v246
	v_mul_f32_e32 v105, v105, v247
	v_mul_f32_e32 v106, v106, v248
	v_mul_f32_e32 v107, v107, v249
	v_cvt_pk_bf16_f32 v100, v108, v109
	v_cvt_pk_bf16_f32 v101, v110, v111
	v_cvt_pk_bf16_f32 v102, v104, v105
	v_cvt_pk_bf16_f32 v103, v106, v107
	v_lshl_add_u64 v[182:183], v[182:183], 0, s[68:69]
	s_nop 0
	global_store_dwordx4 v[182:183], v[100:103], off sc1
	v_exp_f32_e64 v152, -v92
	v_exp_f32_e64 v153, -v93
	v_exp_f32_e64 v178, -v94
	v_exp_f32_e64 v179, -v95
	v_exp_f32_e64 v246, -v88
	v_exp_f32_e64 v247, -v89
	v_exp_f32_e64 v248, -v90
	v_exp_f32_e64 v249, -v91
	v_mul_f32_e32 v92, v92, v84
	v_mul_f32_e32 v93, v93, v85
	v_mul_f32_e32 v94, v94, v86
	v_mul_f32_e32 v95, v95, v87
	v_mul_f32_e32 v88, v88, v80
	v_mul_f32_e32 v89, v89, v81
	v_mul_f32_e32 v90, v90, v82
	v_mul_f32_e32 v91, v91, v83
	v_add_f32_e32 v152, 1.0, v152
	v_add_f32_e32 v153, 1.0, v153
	v_add_f32_e32 v178, 1.0, v178
	v_add_f32_e32 v179, 1.0, v179
	v_add_f32_e32 v246, 1.0, v246
	v_add_f32_e32 v247, 1.0, v247
	v_add_f32_e32 v248, 1.0, v248
	v_add_f32_e32 v249, 1.0, v249
	v_rcp_f32_e32 v152, v152
	v_rcp_f32_e32 v153, v153
	v_rcp_f32_e32 v178, v178
	v_rcp_f32_e32 v179, v179
	v_rcp_f32_e32 v246, v246
	v_rcp_f32_e32 v247, v247
	v_rcp_f32_e32 v248, v248
	v_rcp_f32_e32 v249, v249
	v_mul_f32_e32 v92, v92, v152
	v_mul_f32_e32 v93, v93, v153
	v_mul_f32_e32 v94, v94, v178
	v_mul_f32_e32 v95, v95, v179
	v_mul_f32_e32 v88, v88, v246
	v_mul_f32_e32 v89, v89, v247
	v_mul_f32_e32 v90, v90, v248
	v_mul_f32_e32 v91, v91, v249
	v_cvt_pk_bf16_f32 v84, v92, v93
	v_cvt_pk_bf16_f32 v85, v94, v95
	v_cvt_pk_bf16_f32 v86, v88, v89
	v_cvt_pk_bf16_f32 v87, v90, v91
	v_lshl_add_u64 v[182:183], v[182:183], 0, s[68:69]
	s_nop 0
	global_store_dwordx4 v[182:183], v[84:87], off sc1
	v_exp_f32_e64 v152, -v76
	v_exp_f32_e64 v153, -v77
	v_exp_f32_e64 v178, -v78
	v_exp_f32_e64 v179, -v79
	v_exp_f32_e64 v246, -v72
	v_exp_f32_e64 v247, -v73
	v_exp_f32_e64 v248, -v74
	v_exp_f32_e64 v249, -v75
	v_mul_f32_e32 v76, v76, v68
	v_mul_f32_e32 v77, v77, v69
	v_mul_f32_e32 v78, v78, v70
	v_mul_f32_e32 v79, v79, v71
	v_mul_f32_e32 v72, v72, v64
	v_mul_f32_e32 v73, v73, v65
	v_mul_f32_e32 v74, v74, v66
	v_mul_f32_e32 v75, v75, v67
	v_add_f32_e32 v152, 1.0, v152
	v_add_f32_e32 v153, 1.0, v153
	v_add_f32_e32 v178, 1.0, v178
	v_add_f32_e32 v179, 1.0, v179
	v_add_f32_e32 v246, 1.0, v246
	v_add_f32_e32 v247, 1.0, v247
	v_add_f32_e32 v248, 1.0, v248
	v_add_f32_e32 v249, 1.0, v249
	v_rcp_f32_e32 v152, v152
	v_rcp_f32_e32 v153, v153
	v_rcp_f32_e32 v178, v178
	v_rcp_f32_e32 v179, v179
	v_rcp_f32_e32 v246, v246
	v_rcp_f32_e32 v247, v247
	v_rcp_f32_e32 v248, v248
	v_rcp_f32_e32 v249, v249
	v_mul_f32_e32 v76, v76, v152
	v_mul_f32_e32 v77, v77, v153
	v_mul_f32_e32 v78, v78, v178
	v_mul_f32_e32 v79, v79, v179
	v_mul_f32_e32 v72, v72, v246
	v_mul_f32_e32 v73, v73, v247
	v_mul_f32_e32 v74, v74, v248
	v_mul_f32_e32 v75, v75, v249
	v_cvt_pk_bf16_f32 v68, v76, v77
	v_cvt_pk_bf16_f32 v69, v78, v79
	v_cvt_pk_bf16_f32 v70, v72, v73
	v_cvt_pk_bf16_f32 v71, v74, v75
	v_lshl_add_u64 v[182:183], v[182:183], 0, s[68:69]
	s_nop 0
	global_store_dwordx4 v[182:183], v[68:71], off sc1
	v_exp_f32_e64 v152, -v60
	v_exp_f32_e64 v153, -v61
	v_exp_f32_e64 v178, -v62
	v_exp_f32_e64 v179, -v63
	v_exp_f32_e64 v246, -v56
	v_exp_f32_e64 v247, -v57
	v_exp_f32_e64 v248, -v58
	v_exp_f32_e64 v249, -v59
	v_mul_f32_e32 v60, v60, v52
	v_mul_f32_e32 v61, v61, v53
	v_mul_f32_e32 v62, v62, v54
	v_mul_f32_e32 v63, v63, v55
	v_mul_f32_e32 v56, v56, v48
	v_mul_f32_e32 v57, v57, v49
	v_mul_f32_e32 v58, v58, v50
	v_mul_f32_e32 v59, v59, v51
	v_add_f32_e32 v152, 1.0, v152
	v_add_f32_e32 v153, 1.0, v153
	v_add_f32_e32 v178, 1.0, v178
	v_add_f32_e32 v179, 1.0, v179
	v_add_f32_e32 v246, 1.0, v246
	v_add_f32_e32 v247, 1.0, v247
	v_add_f32_e32 v248, 1.0, v248
	v_add_f32_e32 v249, 1.0, v249
	v_rcp_f32_e32 v152, v152
	v_rcp_f32_e32 v153, v153
	v_rcp_f32_e32 v178, v178
	v_rcp_f32_e32 v179, v179
	v_rcp_f32_e32 v246, v246
	v_rcp_f32_e32 v247, v247
	v_rcp_f32_e32 v248, v248
	v_rcp_f32_e32 v249, v249
	v_mul_f32_e32 v60, v60, v152
	v_mul_f32_e32 v61, v61, v153
	v_mul_f32_e32 v62, v62, v178
	v_mul_f32_e32 v63, v63, v179
	v_mul_f32_e32 v56, v56, v246
	v_mul_f32_e32 v57, v57, v247
	v_mul_f32_e32 v58, v58, v248
	v_mul_f32_e32 v59, v59, v249
	v_cvt_pk_bf16_f32 v52, v60, v61
	v_cvt_pk_bf16_f32 v53, v62, v63
	v_cvt_pk_bf16_f32 v54, v56, v57
	v_cvt_pk_bf16_f32 v55, v58, v59
	v_lshl_add_u64 v[182:183], v[182:183], 0, s[70:71]
	s_nop 0
	global_store_dwordx4 v[182:183], v[52:55], off sc1
	v_exp_f32_e64 v152, -v44
	v_exp_f32_e64 v153, -v45
	v_exp_f32_e64 v178, -v46
	v_exp_f32_e64 v179, -v47
	v_exp_f32_e64 v246, -v40
	v_exp_f32_e64 v247, -v41
	v_exp_f32_e64 v248, -v42
	v_exp_f32_e64 v249, -v43
	v_mul_f32_e32 v44, v44, v36
	v_mul_f32_e32 v45, v45, v37
	v_mul_f32_e32 v46, v46, v38
	v_mul_f32_e32 v47, v47, v39
	v_mul_f32_e32 v40, v40, v32
	v_mul_f32_e32 v41, v41, v33
	v_mul_f32_e32 v42, v42, v34
	v_mul_f32_e32 v43, v43, v35
	v_add_f32_e32 v152, 1.0, v152
	v_add_f32_e32 v153, 1.0, v153
	v_add_f32_e32 v178, 1.0, v178
	v_add_f32_e32 v179, 1.0, v179
	v_add_f32_e32 v246, 1.0, v246
	v_add_f32_e32 v247, 1.0, v247
	v_add_f32_e32 v248, 1.0, v248
	v_add_f32_e32 v249, 1.0, v249
	v_rcp_f32_e32 v152, v152
	v_rcp_f32_e32 v153, v153
	v_rcp_f32_e32 v178, v178
	v_rcp_f32_e32 v179, v179
	v_rcp_f32_e32 v246, v246
	v_rcp_f32_e32 v247, v247
	v_rcp_f32_e32 v248, v248
	v_rcp_f32_e32 v249, v249
	v_mul_f32_e32 v44, v44, v152
	v_mul_f32_e32 v45, v45, v153
	v_mul_f32_e32 v46, v46, v178
	v_mul_f32_e32 v47, v47, v179
	v_mul_f32_e32 v40, v40, v246
	v_mul_f32_e32 v41, v41, v247
	v_mul_f32_e32 v42, v42, v248
	v_mul_f32_e32 v43, v43, v249
	v_cvt_pk_bf16_f32 v36, v44, v45
	v_cvt_pk_bf16_f32 v37, v46, v47
	v_cvt_pk_bf16_f32 v38, v40, v41
	v_cvt_pk_bf16_f32 v39, v42, v43
	v_lshl_add_u64 v[182:183], v[182:183], 0, s[68:69]
	s_nop 0
	global_store_dwordx4 v[182:183], v[36:39], off sc1
	v_exp_f32_e64 v152, -v28
	v_exp_f32_e64 v153, -v29
	v_exp_f32_e64 v178, -v30
	v_exp_f32_e64 v179, -v31
	v_exp_f32_e64 v246, -v24
	v_exp_f32_e64 v247, -v25
	v_exp_f32_e64 v248, -v26
	v_exp_f32_e64 v249, -v27
	v_mul_f32_e32 v28, v28, v20
	v_mul_f32_e32 v29, v29, v21
	v_mul_f32_e32 v30, v30, v22
	v_mul_f32_e32 v31, v31, v23
	v_mul_f32_e32 v24, v24, v16
	v_mul_f32_e32 v25, v25, v17
	v_mul_f32_e32 v26, v26, v18
	v_mul_f32_e32 v27, v27, v19
	v_add_f32_e32 v152, 1.0, v152
	v_add_f32_e32 v153, 1.0, v153
	v_add_f32_e32 v178, 1.0, v178
	v_add_f32_e32 v179, 1.0, v179
	v_add_f32_e32 v246, 1.0, v246
	v_add_f32_e32 v247, 1.0, v247
	v_add_f32_e32 v248, 1.0, v248
	v_add_f32_e32 v249, 1.0, v249
	v_rcp_f32_e32 v152, v152
	v_rcp_f32_e32 v153, v153
	v_rcp_f32_e32 v178, v178
	v_rcp_f32_e32 v179, v179
	v_rcp_f32_e32 v246, v246
	v_rcp_f32_e32 v247, v247
	v_rcp_f32_e32 v248, v248
	v_rcp_f32_e32 v249, v249
	v_mul_f32_e32 v28, v28, v152
	v_mul_f32_e32 v29, v29, v153
	v_mul_f32_e32 v30, v30, v178
	v_mul_f32_e32 v31, v31, v179
	v_mul_f32_e32 v24, v24, v246
	v_mul_f32_e32 v25, v25, v247
	v_mul_f32_e32 v26, v26, v248
	v_mul_f32_e32 v27, v27, v249
	v_cvt_pk_bf16_f32 v20, v28, v29
	v_cvt_pk_bf16_f32 v21, v30, v31
	v_cvt_pk_bf16_f32 v22, v24, v25
	v_cvt_pk_bf16_f32 v23, v26, v27
	v_lshl_add_u64 v[182:183], v[182:183], 0, s[68:69]
	s_nop 0
	global_store_dwordx4 v[182:183], v[20:23], off sc1
	v_exp_f32_e64 v152, -v12
	v_exp_f32_e64 v153, -v13
	v_exp_f32_e64 v178, -v14
	v_exp_f32_e64 v179, -v15
	v_exp_f32_e64 v246, -v8
	v_exp_f32_e64 v247, -v9
	v_exp_f32_e64 v248, -v10
	v_exp_f32_e64 v249, -v11
	v_mul_f32_e32 v12, v12, v4
	v_mul_f32_e32 v13, v13, v5
	v_mul_f32_e32 v14, v14, v6
	v_mul_f32_e32 v15, v15, v7
	v_mul_f32_e32 v8, v8, v0
	v_mul_f32_e32 v9, v9, v1
	v_mul_f32_e32 v10, v10, v2
	v_mul_f32_e32 v11, v11, v3
	v_add_f32_e32 v152, 1.0, v152
	v_add_f32_e32 v153, 1.0, v153
	v_add_f32_e32 v178, 1.0, v178
	v_add_f32_e32 v179, 1.0, v179
	v_add_f32_e32 v246, 1.0, v246
	v_add_f32_e32 v247, 1.0, v247
	v_add_f32_e32 v248, 1.0, v248
	v_add_f32_e32 v249, 1.0, v249
	v_rcp_f32_e32 v152, v152
	v_rcp_f32_e32 v153, v153
	v_rcp_f32_e32 v178, v178
	v_rcp_f32_e32 v179, v179
	v_rcp_f32_e32 v246, v246
	v_rcp_f32_e32 v247, v247
	v_rcp_f32_e32 v248, v248
	v_rcp_f32_e32 v249, v249
	v_mul_f32_e32 v12, v12, v152
	v_mul_f32_e32 v13, v13, v153
	v_mul_f32_e32 v14, v14, v178
	v_mul_f32_e32 v15, v15, v179
	v_mul_f32_e32 v8, v8, v246
	v_mul_f32_e32 v9, v9, v247
	v_mul_f32_e32 v10, v10, v248
	v_mul_f32_e32 v11, v11, v249
	v_cvt_pk_bf16_f32 v4, v12, v13
	v_cvt_pk_bf16_f32 v5, v14, v15
	v_cvt_pk_bf16_f32 v6, v8, v9
	v_cvt_pk_bf16_f32 v7, v10, v11
	v_lshl_add_u64 v[182:183], v[182:183], 0, s[68:69]
	s_nop 0
	global_store_dwordx4 v[182:183], v[4:7], off sc1
	s_cbranch_vccnz .LBB0_209
	s_andn2_b64 vcc, exec, s[4:5]
	s_cbranch_vccnz .LBB0_208
	s_barrier
	s_branch .LBB0_208

.LBB0_1441:
	v_lshl_add_u32 v181, s1, 8, v154
	v_lshl_or_b32 v170, s0, 7, v156
	v_readlane_b32 s0, v254, 45
	v_readlane_b32 s1, v254, 46
	s_movk_i32 s3, 0x1600
	s_mov_b64 s[68:69], 0x16000
	s_mov_b64 s[70:71], 0x6e000
	s_andn2_b64 vcc, exec, s[40:41]
	s_mov_b64 s[16:17], -1
	v_ashrrev_i32_e32 v171, 31, v170
	v_mov_b64_e32 v[152:153], s[0:1]
	v_lshlrev_b64 v[170:171], 1, v[170:171]
	v_mad_i64_i32 v[182:183], s[0:1], v181, s3, v[152:153]
	s_nop 0
	v_lshl_add_u64 v[182:183], v[182:183], 0, v[170:171]
	v_exp_f32_e64 v152, -v124
	v_exp_f32_e64 v153, -v125
	v_exp_f32_e64 v178, -v126
	v_exp_f32_e64 v179, -v127
	v_exp_f32_e64 v246, -v120
	v_exp_f32_e64 v247, -v121
	v_exp_f32_e64 v248, -v122
	v_exp_f32_e64 v249, -v123
	v_mul_f32_e32 v124, v124, v116
	v_mul_f32_e32 v125, v125, v117
	v_mul_f32_e32 v126, v126, v118
	v_mul_f32_e32 v127, v127, v119
	v_mul_f32_e32 v120, v120, v112
	v_mul_f32_e32 v121, v121, v113
	v_mul_f32_e32 v122, v122, v114
	v_mul_f32_e32 v123, v123, v115
	v_add_f32_e32 v152, 1.0, v152
	v_add_f32_e32 v153, 1.0, v153
	v_add_f32_e32 v178, 1.0, v178
	v_add_f32_e32 v179, 1.0, v179
	v_add_f32_e32 v246, 1.0, v246
	v_add_f32_e32 v247, 1.0, v247
	v_add_f32_e32 v248, 1.0, v248
	v_add_f32_e32 v249, 1.0, v249
	v_rcp_f32_e32 v152, v152
	v_rcp_f32_e32 v153, v153
	v_rcp_f32_e32 v178, v178
	v_rcp_f32_e32 v179, v179
	v_rcp_f32_e32 v246, v246
	v_rcp_f32_e32 v247, v247
	v_rcp_f32_e32 v248, v248
	v_rcp_f32_e32 v249, v249
	v_mul_f32_e32 v124, v124, v152
	v_mul_f32_e32 v125, v125, v153
	v_mul_f32_e32 v126, v126, v178
	v_mul_f32_e32 v127, v127, v179
	v_mul_f32_e32 v120, v120, v246
	v_mul_f32_e32 v121, v121, v247
	v_mul_f32_e32 v122, v122, v248
	v_mul_f32_e32 v123, v123, v249
	v_cvt_pk_bf16_f32 v116, v124, v125
	v_cvt_pk_bf16_f32 v117, v126, v127
	v_cvt_pk_bf16_f32 v118, v120, v121
	v_cvt_pk_bf16_f32 v119, v122, v123
	global_store_dwordx4 v[182:183], v[116:119], off sc1
	v_exp_f32_e64 v152, -v108
	v_exp_f32_e64 v153, -v109
	v_exp_f32_e64 v178, -v110
	v_exp_f32_e64 v179, -v111
	v_exp_f32_e64 v246, -v104
	v_exp_f32_e64 v247, -v105
	v_exp_f32_e64 v248, -v106
	v_exp_f32_e64 v249, -v107
	v_mul_f32_e32 v108, v108, v100
	v_mul_f32_e32 v109, v109, v101
	v_mul_f32_e32 v110, v110, v102
	v_mul_f32_e32 v111, v111, v103
	v_mul_f32_e32 v104, v104, v96
	v_mul_f32_e32 v105, v105, v97
	v_mul_f32_e32 v106, v106, v98
	v_mul_f32_e32 v107, v107, v99
	v_add_f32_e32 v152, 1.0, v152
	v_add_f32_e32 v153, 1.0, v153
	v_add_f32_e32 v178, 1.0, v178
	v_add_f32_e32 v179, 1.0, v179
	v_add_f32_e32 v246, 1.0, v246
	v_add_f32_e32 v247, 1.0, v247
	v_add_f32_e32 v248, 1.0, v248
	v_add_f32_e32 v249, 1.0, v249
	v_rcp_f32_e32 v152, v152
	v_rcp_f32_e32 v153, v153
	v_rcp_f32_e32 v178, v178
	v_rcp_f32_e32 v179, v179
	v_rcp_f32_e32 v246, v246
	v_rcp_f32_e32 v247, v247
	v_rcp_f32_e32 v248, v248
	v_rcp_f32_e32 v249, v249
	v_mul_f32_e32 v108, v108, v152
	v_mul_f32_e32 v109, v109, v153
	v_mul_f32_e32 v110, v110, v178
	v_mul_f32_e32 v111, v111, v179
	v_mul_f32_e32 v104, v104, v246
	v_mul_f32_e32 v105, v105, v247
	v_mul_f32_e32 v106, v106, v248
	v_mul_f32_e32 v107, v107, v249
	v_cvt_pk_bf16_f32 v100, v108, v109
	v_cvt_pk_bf16_f32 v101, v110, v111
	v_cvt_pk_bf16_f32 v102, v104, v105
	v_cvt_pk_bf16_f32 v103, v106, v107
	v_lshl_add_u64 v[182:183], v[182:183], 0, s[68:69]
	s_nop 0
	global_store_dwordx4 v[182:183], v[100:103], off sc1
	v_exp_f32_e64 v152, -v92
	v_exp_f32_e64 v153, -v93
	v_exp_f32_e64 v178, -v94
	v_exp_f32_e64 v179, -v95
	v_exp_f32_e64 v246, -v88
	v_exp_f32_e64 v247, -v89
	v_exp_f32_e64 v248, -v90
	v_exp_f32_e64 v249, -v91
	v_mul_f32_e32 v92, v92, v84
	v_mul_f32_e32 v93, v93, v85
	v_mul_f32_e32 v94, v94, v86
	v_mul_f32_e32 v95, v95, v87
	v_mul_f32_e32 v88, v88, v80
	v_mul_f32_e32 v89, v89, v81
	v_mul_f32_e32 v90, v90, v82
	v_mul_f32_e32 v91, v91, v83
	v_add_f32_e32 v152, 1.0, v152
	v_add_f32_e32 v153, 1.0, v153
	v_add_f32_e32 v178, 1.0, v178
	v_add_f32_e32 v179, 1.0, v179
	v_add_f32_e32 v246, 1.0, v246
	v_add_f32_e32 v247, 1.0, v247
	v_add_f32_e32 v248, 1.0, v248
	v_add_f32_e32 v249, 1.0, v249
	v_rcp_f32_e32 v152, v152
	v_rcp_f32_e32 v153, v153
	v_rcp_f32_e32 v178, v178
	v_rcp_f32_e32 v179, v179
	v_rcp_f32_e32 v246, v246
	v_rcp_f32_e32 v247, v247
	v_rcp_f32_e32 v248, v248
	v_rcp_f32_e32 v249, v249
	v_mul_f32_e32 v92, v92, v152
	v_mul_f32_e32 v93, v93, v153
	v_mul_f32_e32 v94, v94, v178
	v_mul_f32_e32 v95, v95, v179
	v_mul_f32_e32 v88, v88, v246
	v_mul_f32_e32 v89, v89, v247
	v_mul_f32_e32 v90, v90, v248
	v_mul_f32_e32 v91, v91, v249
	v_cvt_pk_bf16_f32 v84, v92, v93
	v_cvt_pk_bf16_f32 v85, v94, v95
	v_cvt_pk_bf16_f32 v86, v88, v89
	v_cvt_pk_bf16_f32 v87, v90, v91
	v_lshl_add_u64 v[182:183], v[182:183], 0, s[68:69]
	s_nop 0
	global_store_dwordx4 v[182:183], v[84:87], off sc1
	v_exp_f32_e64 v152, -v76
	v_exp_f32_e64 v153, -v77
	v_exp_f32_e64 v178, -v78
	v_exp_f32_e64 v179, -v79
	v_exp_f32_e64 v246, -v72
	v_exp_f32_e64 v247, -v73
	v_exp_f32_e64 v248, -v74
	v_exp_f32_e64 v249, -v75
	v_mul_f32_e32 v76, v76, v68
	v_mul_f32_e32 v77, v77, v69
	v_mul_f32_e32 v78, v78, v70
	v_mul_f32_e32 v79, v79, v71
	v_mul_f32_e32 v72, v72, v64
	v_mul_f32_e32 v73, v73, v65
	v_mul_f32_e32 v74, v74, v66
	v_mul_f32_e32 v75, v75, v67
	v_add_f32_e32 v152, 1.0, v152
	v_add_f32_e32 v153, 1.0, v153
	v_add_f32_e32 v178, 1.0, v178
	v_add_f32_e32 v179, 1.0, v179
	v_add_f32_e32 v246, 1.0, v246
	v_add_f32_e32 v247, 1.0, v247
	v_add_f32_e32 v248, 1.0, v248
	v_add_f32_e32 v249, 1.0, v249
	v_rcp_f32_e32 v152, v152
	v_rcp_f32_e32 v153, v153
	v_rcp_f32_e32 v178, v178
	v_rcp_f32_e32 v179, v179
	v_rcp_f32_e32 v246, v246
	v_rcp_f32_e32 v247, v247
	v_rcp_f32_e32 v248, v248
	v_rcp_f32_e32 v249, v249
	v_mul_f32_e32 v76, v76, v152
	v_mul_f32_e32 v77, v77, v153
	v_mul_f32_e32 v78, v78, v178
	v_mul_f32_e32 v79, v79, v179
	v_mul_f32_e32 v72, v72, v246
	v_mul_f32_e32 v73, v73, v247
	v_mul_f32_e32 v74, v74, v248
	v_mul_f32_e32 v75, v75, v249
	v_cvt_pk_bf16_f32 v68, v76, v77
	v_cvt_pk_bf16_f32 v69, v78, v79
	v_cvt_pk_bf16_f32 v70, v72, v73
	v_cvt_pk_bf16_f32 v71, v74, v75
	v_lshl_add_u64 v[182:183], v[182:183], 0, s[68:69]
	s_nop 0
	global_store_dwordx4 v[182:183], v[68:71], off sc1
	v_exp_f32_e64 v152, -v60
	v_exp_f32_e64 v153, -v61
	v_exp_f32_e64 v178, -v62
	v_exp_f32_e64 v179, -v63
	v_exp_f32_e64 v246, -v56
	v_exp_f32_e64 v247, -v57
	v_exp_f32_e64 v248, -v58
	v_exp_f32_e64 v249, -v59
	v_mul_f32_e32 v60, v60, v52
	v_mul_f32_e32 v61, v61, v53
	v_mul_f32_e32 v62, v62, v54
	v_mul_f32_e32 v63, v63, v55
	v_mul_f32_e32 v56, v56, v48
	v_mul_f32_e32 v57, v57, v49
	v_mul_f32_e32 v58, v58, v50
	v_mul_f32_e32 v59, v59, v51
	v_add_f32_e32 v152, 1.0, v152
	v_add_f32_e32 v153, 1.0, v153
	v_add_f32_e32 v178, 1.0, v178
	v_add_f32_e32 v179, 1.0, v179
	v_add_f32_e32 v246, 1.0, v246
	v_add_f32_e32 v247, 1.0, v247
	v_add_f32_e32 v248, 1.0, v248
	v_add_f32_e32 v249, 1.0, v249
	v_rcp_f32_e32 v152, v152
	v_rcp_f32_e32 v153, v153
	v_rcp_f32_e32 v178, v178
	v_rcp_f32_e32 v179, v179
	v_rcp_f32_e32 v246, v246
	v_rcp_f32_e32 v247, v247
	v_rcp_f32_e32 v248, v248
	v_rcp_f32_e32 v249, v249
	v_mul_f32_e32 v60, v60, v152
	v_mul_f32_e32 v61, v61, v153
	v_mul_f32_e32 v62, v62, v178
	v_mul_f32_e32 v63, v63, v179
	v_mul_f32_e32 v56, v56, v246
	v_mul_f32_e32 v57, v57, v247
	v_mul_f32_e32 v58, v58, v248
	v_mul_f32_e32 v59, v59, v249
	v_cvt_pk_bf16_f32 v52, v60, v61
	v_cvt_pk_bf16_f32 v53, v62, v63
	v_cvt_pk_bf16_f32 v54, v56, v57
	v_cvt_pk_bf16_f32 v55, v58, v59
	v_lshl_add_u64 v[182:183], v[182:183], 0, s[70:71]
	s_nop 0
	global_store_dwordx4 v[182:183], v[52:55], off sc1
	v_exp_f32_e64 v152, -v44
	v_exp_f32_e64 v153, -v45
	v_exp_f32_e64 v178, -v46
	v_exp_f32_e64 v179, -v47
	v_exp_f32_e64 v246, -v40
	v_exp_f32_e64 v247, -v41
	v_exp_f32_e64 v248, -v42
	v_exp_f32_e64 v249, -v43
	v_mul_f32_e32 v44, v44, v36
	v_mul_f32_e32 v45, v45, v37
	v_mul_f32_e32 v46, v46, v38
	v_mul_f32_e32 v47, v47, v39
	v_mul_f32_e32 v40, v40, v32
	v_mul_f32_e32 v41, v41, v33
	v_mul_f32_e32 v42, v42, v34
	v_mul_f32_e32 v43, v43, v35
	v_add_f32_e32 v152, 1.0, v152
	v_add_f32_e32 v153, 1.0, v153
	v_add_f32_e32 v178, 1.0, v178
	v_add_f32_e32 v179, 1.0, v179
	v_add_f32_e32 v246, 1.0, v246
	v_add_f32_e32 v247, 1.0, v247
	v_add_f32_e32 v248, 1.0, v248
	v_add_f32_e32 v249, 1.0, v249
	v_rcp_f32_e32 v152, v152
	v_rcp_f32_e32 v153, v153
	v_rcp_f32_e32 v178, v178
	v_rcp_f32_e32 v179, v179
	v_rcp_f32_e32 v246, v246
	v_rcp_f32_e32 v247, v247
	v_rcp_f32_e32 v248, v248
	v_rcp_f32_e32 v249, v249
	v_mul_f32_e32 v44, v44, v152
	v_mul_f32_e32 v45, v45, v153
	v_mul_f32_e32 v46, v46, v178
	v_mul_f32_e32 v47, v47, v179
	v_mul_f32_e32 v40, v40, v246
	v_mul_f32_e32 v41, v41, v247
	v_mul_f32_e32 v42, v42, v248
	v_mul_f32_e32 v43, v43, v249
	v_cvt_pk_bf16_f32 v36, v44, v45
	v_cvt_pk_bf16_f32 v37, v46, v47
	v_cvt_pk_bf16_f32 v38, v40, v41
	v_cvt_pk_bf16_f32 v39, v42, v43
	v_lshl_add_u64 v[182:183], v[182:183], 0, s[68:69]
	s_nop 0
	global_store_dwordx4 v[182:183], v[36:39], off sc1
	v_exp_f32_e64 v152, -v28
	v_exp_f32_e64 v153, -v29
	v_exp_f32_e64 v178, -v30
	v_exp_f32_e64 v179, -v31
	v_exp_f32_e64 v246, -v24
	v_exp_f32_e64 v247, -v25
	v_exp_f32_e64 v248, -v26
	v_exp_f32_e64 v249, -v27
	v_mul_f32_e32 v28, v28, v20
	v_mul_f32_e32 v29, v29, v21
	v_mul_f32_e32 v30, v30, v22
	v_mul_f32_e32 v31, v31, v23
	v_mul_f32_e32 v24, v24, v16
	v_mul_f32_e32 v25, v25, v17
	v_mul_f32_e32 v26, v26, v18
	v_mul_f32_e32 v27, v27, v19
	v_add_f32_e32 v152, 1.0, v152
	v_add_f32_e32 v153, 1.0, v153
	v_add_f32_e32 v178, 1.0, v178
	v_add_f32_e32 v179, 1.0, v179
	v_add_f32_e32 v246, 1.0, v246
	v_add_f32_e32 v247, 1.0, v247
	v_add_f32_e32 v248, 1.0, v248
	v_add_f32_e32 v249, 1.0, v249
	v_rcp_f32_e32 v152, v152
	v_rcp_f32_e32 v153, v153
	v_rcp_f32_e32 v178, v178
	v_rcp_f32_e32 v179, v179
	v_rcp_f32_e32 v246, v246
	v_rcp_f32_e32 v247, v247
	v_rcp_f32_e32 v248, v248
	v_rcp_f32_e32 v249, v249
	v_mul_f32_e32 v28, v28, v152
	v_mul_f32_e32 v29, v29, v153
	v_mul_f32_e32 v30, v30, v178
	v_mul_f32_e32 v31, v31, v179
	v_mul_f32_e32 v24, v24, v246
	v_mul_f32_e32 v25, v25, v247
	v_mul_f32_e32 v26, v26, v248
	v_mul_f32_e32 v27, v27, v249
	v_cvt_pk_bf16_f32 v20, v28, v29
	v_cvt_pk_bf16_f32 v21, v30, v31
	v_cvt_pk_bf16_f32 v22, v24, v25
	v_cvt_pk_bf16_f32 v23, v26, v27
	v_lshl_add_u64 v[182:183], v[182:183], 0, s[68:69]
	s_nop 0
	global_store_dwordx4 v[182:183], v[20:23], off sc1
	v_exp_f32_e64 v152, -v12
	v_exp_f32_e64 v153, -v13
	v_exp_f32_e64 v178, -v14
	v_exp_f32_e64 v179, -v15
	v_exp_f32_e64 v246, -v8
	v_exp_f32_e64 v247, -v9
	v_exp_f32_e64 v248, -v10
	v_exp_f32_e64 v249, -v11
	v_mul_f32_e32 v12, v12, v4
	v_mul_f32_e32 v13, v13, v5
	v_mul_f32_e32 v14, v14, v6
	v_mul_f32_e32 v15, v15, v7
	v_mul_f32_e32 v8, v8, v0
	v_mul_f32_e32 v9, v9, v1
	v_mul_f32_e32 v10, v10, v2
	v_mul_f32_e32 v11, v11, v3
	v_add_f32_e32 v152, 1.0, v152
	v_add_f32_e32 v153, 1.0, v153
	v_add_f32_e32 v178, 1.0, v178
	v_add_f32_e32 v179, 1.0, v179
	v_add_f32_e32 v246, 1.0, v246
	v_add_f32_e32 v247, 1.0, v247
	v_add_f32_e32 v248, 1.0, v248
	v_add_f32_e32 v249, 1.0, v249
	v_rcp_f32_e32 v152, v152
	v_rcp_f32_e32 v153, v153
	v_rcp_f32_e32 v178, v178
	v_rcp_f32_e32 v179, v179
	v_rcp_f32_e32 v246, v246
	v_rcp_f32_e32 v247, v247
	v_rcp_f32_e32 v248, v248
	v_rcp_f32_e32 v249, v249
	v_mul_f32_e32 v12, v12, v152
	v_mul_f32_e32 v13, v13, v153
	v_mul_f32_e32 v14, v14, v178
	v_mul_f32_e32 v15, v15, v179
	v_mul_f32_e32 v8, v8, v246
	v_mul_f32_e32 v9, v9, v247
	v_mul_f32_e32 v10, v10, v248
	v_mul_f32_e32 v11, v11, v249
	v_cvt_pk_bf16_f32 v4, v12, v13
	v_cvt_pk_bf16_f32 v5, v14, v15
	v_cvt_pk_bf16_f32 v6, v8, v9
	v_cvt_pk_bf16_f32 v7, v10, v11
	v_lshl_add_u64 v[182:183], v[182:183], 0, s[68:69]
	s_nop 0
	global_store_dwordx4 v[182:183], v[4:7], off sc1
	s_cbranch_vccnz .LBB0_1434
	s_andn2_b64 vcc, exec, s[4:5]
	s_cbranch_vccnz .LBB0_1433
	s_barrier
	s_branch .LBB0_1433
